# last-layer epilogue pass 2: row sums and g_final fragments fetched once up front instead of per row behind vmcnt waits
# speedup vs baseline: 1.0119x; 1.0051x over previous
.LBB0_818:
	s_or_b64 exec, exec, s[34:35]
	s_barrier
	v_lshl_add_u64 v[140:141], v[140:141], 2, s[18:19]
	global_load_dword v218, v[112:113], off sc1
	global_load_dword v219, v[148:149], off sc1
	global_load_dword v220, v[154:155], off sc1
	global_load_dword v221, v[158:159], off sc1
	global_load_dword v222, v[112:113], off offset:512 sc1
	global_load_dword v223, v[112:113], off offset:576 sc1
	global_load_dword v230, v[112:113], off offset:640 sc1
	global_load_dword v231, v[112:113], off offset:704 sc1
	global_load_dwordx4 v[202:205], v[140:141], off
	global_load_dwordx4 v[206:209], v[140:141], off offset:16
	global_load_dwordx4 v[210:213], v[140:141], off offset:512
	global_load_dwordx4 v[214:217], v[140:141], off offset:528
	s_waitcnt vmcnt(0)
	v_mov_b32_e32 v152, v218
	v_mov_b64_e32 v[172:173], v[202:203]
	v_mov_b64_e32 v[174:175], v[204:205]
	v_mov_b64_e32 v[176:177], v[206:207]
	v_mov_b64_e32 v[178:179], v[208:209]
	s_mov_b64 s[34:35], -1
	v_fmamk_f32 v152, v152, 0x3a800000, v192
	v_mul_f32_e32 v153, 0x4b800000, v152
	v_cmp_gt_f32_e32 vcc, s93, v152
	s_nop 1
	v_cndmask_b32_e32 v152, v152, v153, vcc
	v_rsq_f32_e32 v152, v152
	s_nop 0
	v_mul_f32_e32 v153, 0x45800000, v152
	v_cndmask_b32_e32 v152, v152, v153, vcc
	v_pk_mul_f32 v[124:125], v[124:125], v[152:153] op_sel_hi:[1,0]
	v_pk_mul_f32 v[126:127], v[126:127], v[152:153] op_sel_hi:[1,0]
	v_pk_mul_f32 v[166:167], v[120:121], v[152:153] op_sel_hi:[1,0]
	v_pk_mul_f32 v[180:181], v[122:123], v[152:153] op_sel_hi:[1,0]
	v_pk_mul_f32 v[122:123], v[174:175], v[126:127]
	v_pk_mul_f32 v[120:121], v[172:173], v[124:125]
	v_pk_mul_f32 v[126:127], v[178:179], v[180:181]
	v_pk_mul_f32 v[124:125], v[176:177], v[166:167]
	global_store_dwordx4 v[138:139], v[120:123], off
	global_store_dwordx4 v[138:139], v[124:127], off offset:16
	v_mov_b64_e32 v[120:121], v[210:211]
	v_mov_b64_e32 v[122:123], v[212:213]
	s_nop 0
	v_mov_b64_e32 v[124:125], v[214:215]
	v_mov_b64_e32 v[126:127], v[216:217]
	v_pk_mul_f32 v[142:143], v[142:143], v[152:153] op_sel_hi:[1,0]
	v_pk_mul_f32 v[144:145], v[144:145], v[152:153] op_sel_hi:[1,0]
	v_pk_mul_f32 v[166:167], v[116:117], v[152:153] op_sel_hi:[1,0]
	v_pk_mul_f32 v[152:153], v[118:119], v[152:153] op_sel_hi:[1,0]
	v_pk_mul_f32 v[116:117], v[120:121], v[144:145]
	v_pk_mul_f32 v[118:119], v[122:123], v[142:143]
	v_pk_mul_f32 v[120:121], v[124:125], v[152:153]
	v_pk_mul_f32 v[122:123], v[126:127], v[166:167]
	global_store_dwordx4 v[138:139], v[116:119], off offset:512
	global_store_dwordx4 v[138:139], v[120:123], off offset:528
	v_mov_b32_e32 v124, v219
	s_nop 0
	v_mov_b64_e32 v[116:117], v[202:203]
	v_mov_b64_e32 v[118:119], v[204:205]
	v_mov_b64_e32 v[120:121], v[206:207]
	v_mov_b64_e32 v[122:123], v[208:209]
	v_fmamk_f32 v124, v124, 0x3a800000, v192
	v_mul_f32_e32 v125, 0x4b800000, v124
	v_cmp_gt_f32_e32 vcc, s93, v124
	s_nop 1
	v_cndmask_b32_e32 v124, v124, v125, vcc
	v_rsq_f32_e32 v124, v124
	s_nop 0
	v_mul_f32_e32 v125, 0x45800000, v124
	v_cndmask_b32_e32 v124, v124, v125, vcc
	v_pk_mul_f32 v[108:109], v[108:109], v[124:125] op_sel_hi:[1,0]
	v_pk_mul_f32 v[110:111], v[110:111], v[124:125] op_sel_hi:[1,0]
	v_pk_mul_f32 v[126:127], v[104:105], v[124:125] op_sel_hi:[1,0]
	v_pk_mul_f32 v[138:139], v[106:107], v[124:125] op_sel_hi:[1,0]
	v_pk_mul_f32 v[106:107], v[118:119], v[110:111]
	v_pk_mul_f32 v[104:105], v[116:117], v[108:109]
	v_pk_mul_f32 v[110:111], v[122:123], v[138:139]
	v_pk_mul_f32 v[108:109], v[120:121], v[126:127]
	global_store_dwordx4 v[114:115], v[104:107], off
	global_store_dwordx4 v[114:115], v[108:111], off offset:16
	v_mov_b64_e32 v[104:105], v[210:211]
	v_mov_b64_e32 v[106:107], v[212:213]
	s_nop 0
	v_mov_b64_e32 v[108:109], v[214:215]
	v_mov_b64_e32 v[110:111], v[216:217]
	v_pk_mul_f32 v[102:103], v[102:103], v[124:125] op_sel_hi:[1,0]
	v_pk_mul_f32 v[116:117], v[146:147], v[124:125] op_sel_hi:[1,0]
	v_pk_mul_f32 v[118:119], v[98:99], v[124:125] op_sel_hi:[1,0]
	v_pk_mul_f32 v[120:121], v[100:101], v[124:125] op_sel_hi:[1,0]
	v_pk_mul_f32 v[98:99], v[104:105], v[116:117]
	v_pk_mul_f32 v[100:101], v[106:107], v[102:103]
	v_pk_mul_f32 v[102:103], v[108:109], v[120:121]
	v_pk_mul_f32 v[104:105], v[110:111], v[118:119]
	global_store_dwordx4 v[114:115], v[98:101], off offset:512
	global_store_dwordx4 v[114:115], v[102:105], off offset:528
	v_mov_b32_e32 v106, v220
	s_nop 0
	v_mov_b64_e32 v[98:99], v[202:203]
	v_mov_b64_e32 v[100:101], v[204:205]
	v_mov_b64_e32 v[102:103], v[206:207]
	v_mov_b64_e32 v[104:105], v[208:209]
	v_fmamk_f32 v106, v106, 0x3a800000, v192
	v_mul_f32_e32 v107, 0x4b800000, v106
	v_cmp_gt_f32_e32 vcc, s93, v106
	s_nop 1
	v_cndmask_b32_e32 v106, v106, v107, vcc
	v_rsq_f32_e32 v106, v106
	s_nop 0
	v_mul_f32_e32 v107, 0x45800000, v106
	v_cndmask_b32_e32 v106, v106, v107, vcc
	v_pk_mul_f32 v[92:93], v[92:93], v[106:107] op_sel_hi:[1,0]
	v_pk_mul_f32 v[94:95], v[94:95], v[106:107] op_sel_hi:[1,0]
	v_pk_mul_f32 v[108:109], v[88:89], v[106:107] op_sel_hi:[1,0]
	v_pk_mul_f32 v[110:111], v[90:91], v[106:107] op_sel_hi:[1,0]
	v_pk_mul_f32 v[90:91], v[100:101], v[94:95]
	v_pk_mul_f32 v[88:89], v[98:99], v[92:93]
	v_pk_mul_f32 v[94:95], v[104:105], v[110:111]
	v_pk_mul_f32 v[92:93], v[102:103], v[108:109]
	global_store_dwordx4 v[96:97], v[88:91], off
	global_store_dwordx4 v[96:97], v[92:95], off offset:16
	v_mov_b64_e32 v[88:89], v[210:211]
	v_mov_b64_e32 v[90:91], v[212:213]
	s_nop 0
	v_mov_b64_e32 v[92:93], v[214:215]
	v_mov_b64_e32 v[94:95], v[216:217]
	v_pk_mul_f32 v[86:87], v[86:87], v[106:107] op_sel_hi:[1,0]
	v_pk_mul_f32 v[98:99], v[150:151], v[106:107] op_sel_hi:[1,0]
	v_pk_mul_f32 v[100:101], v[82:83], v[106:107] op_sel_hi:[1,0]
	v_pk_mul_f32 v[102:103], v[84:85], v[106:107] op_sel_hi:[1,0]
	v_pk_mul_f32 v[82:83], v[88:89], v[98:99]
	v_pk_mul_f32 v[84:85], v[90:91], v[86:87]
	v_pk_mul_f32 v[86:87], v[92:93], v[102:103]
	v_pk_mul_f32 v[88:89], v[94:95], v[100:101]
	global_store_dwordx4 v[96:97], v[82:85], off offset:512
	global_store_dwordx4 v[96:97], v[86:89], off offset:528
	v_mov_b32_e32 v90, v221
	s_nop 0
	v_mov_b64_e32 v[82:83], v[202:203]
	v_mov_b64_e32 v[84:85], v[204:205]
	v_mov_b64_e32 v[86:87], v[206:207]
	v_mov_b64_e32 v[88:89], v[208:209]
	v_fmamk_f32 v90, v90, 0x3a800000, v192
	v_mul_f32_e32 v91, 0x4b800000, v90
	v_cmp_gt_f32_e32 vcc, s93, v90
	s_nop 1
	v_cndmask_b32_e32 v90, v90, v91, vcc
	v_rsq_f32_e32 v90, v90
	s_nop 0
	v_mul_f32_e32 v91, 0x45800000, v90
	v_cndmask_b32_e32 v90, v90, v91, vcc
	v_pk_mul_f32 v[76:77], v[76:77], v[90:91] op_sel_hi:[1,0]
	v_pk_mul_f32 v[78:79], v[78:79], v[90:91] op_sel_hi:[1,0]
	v_pk_mul_f32 v[92:93], v[72:73], v[90:91] op_sel_hi:[1,0]
	v_pk_mul_f32 v[94:95], v[74:75], v[90:91] op_sel_hi:[1,0]
	v_pk_mul_f32 v[74:75], v[84:85], v[78:79]
	v_pk_mul_f32 v[72:73], v[82:83], v[76:77]
	v_pk_mul_f32 v[78:79], v[88:89], v[94:95]
	v_pk_mul_f32 v[76:77], v[86:87], v[92:93]
	global_store_dwordx4 v[80:81], v[72:75], off
	global_store_dwordx4 v[80:81], v[76:79], off offset:16
	v_mov_b64_e32 v[72:73], v[210:211]
	v_mov_b64_e32 v[74:75], v[212:213]
	s_nop 0
	v_mov_b64_e32 v[76:77], v[214:215]
	v_mov_b64_e32 v[78:79], v[216:217]
	v_pk_mul_f32 v[70:71], v[70:71], v[90:91] op_sel_hi:[1,0]
	v_pk_mul_f32 v[82:83], v[156:157], v[90:91] op_sel_hi:[1,0]
	v_pk_mul_f32 v[84:85], v[66:67], v[90:91] op_sel_hi:[1,0]
	v_pk_mul_f32 v[86:87], v[68:69], v[90:91] op_sel_hi:[1,0]
	v_pk_mul_f32 v[66:67], v[72:73], v[82:83]
	v_pk_mul_f32 v[68:69], v[74:75], v[70:71]
	v_pk_mul_f32 v[70:71], v[76:77], v[86:87]
	v_pk_mul_f32 v[72:73], v[78:79], v[84:85]
	global_store_dwordx4 v[80:81], v[66:69], off offset:512
	global_store_dwordx4 v[80:81], v[70:73], off offset:528
	v_mov_b32_e32 v74, v222
	s_nop 0
	v_mov_b64_e32 v[66:67], v[202:203]
	v_mov_b64_e32 v[68:69], v[204:205]
	v_mov_b64_e32 v[70:71], v[206:207]
	v_mov_b64_e32 v[72:73], v[208:209]
	v_fmamk_f32 v74, v74, 0x3a800000, v192
	v_mul_f32_e32 v75, 0x4b800000, v74
	v_cmp_gt_f32_e32 vcc, s93, v74
	s_nop 1
	v_cndmask_b32_e32 v74, v74, v75, vcc
	v_rsq_f32_e32 v74, v74
	s_nop 0
	v_mul_f32_e32 v75, 0x45800000, v74
	v_cndmask_b32_e32 v74, v74, v75, vcc
	v_pk_mul_f32 v[60:61], v[60:61], v[74:75] op_sel_hi:[1,0]
	v_pk_mul_f32 v[62:63], v[62:63], v[74:75] op_sel_hi:[1,0]
	v_pk_mul_f32 v[76:77], v[56:57], v[74:75] op_sel_hi:[1,0]
	v_pk_mul_f32 v[78:79], v[58:59], v[74:75] op_sel_hi:[1,0]
	v_pk_mul_f32 v[58:59], v[68:69], v[62:63]
	v_pk_mul_f32 v[56:57], v[66:67], v[60:61]
	v_pk_mul_f32 v[62:63], v[72:73], v[78:79]
	v_pk_mul_f32 v[60:61], v[70:71], v[76:77]
	global_store_dwordx4 v[64:65], v[56:59], off
	global_store_dwordx4 v[64:65], v[60:63], off offset:16
	v_mov_b64_e32 v[56:57], v[210:211]
	v_mov_b64_e32 v[58:59], v[212:213]
	s_nop 0
	v_mov_b64_e32 v[60:61], v[214:215]
	v_mov_b64_e32 v[62:63], v[216:217]
	v_pk_mul_f32 v[54:55], v[54:55], v[74:75] op_sel_hi:[1,0]
	v_pk_mul_f32 v[66:67], v[160:161], v[74:75] op_sel_hi:[1,0]
	v_pk_mul_f32 v[68:69], v[50:51], v[74:75] op_sel_hi:[1,0]
	v_pk_mul_f32 v[70:71], v[52:53], v[74:75] op_sel_hi:[1,0]
	v_pk_mul_f32 v[50:51], v[56:57], v[66:67]
	v_pk_mul_f32 v[52:53], v[58:59], v[54:55]
	v_pk_mul_f32 v[54:55], v[60:61], v[70:71]
	v_pk_mul_f32 v[56:57], v[62:63], v[68:69]
	global_store_dwordx4 v[64:65], v[50:53], off offset:512
	global_store_dwordx4 v[64:65], v[54:57], off offset:528
	v_mov_b32_e32 v58, v223
	s_nop 0
	v_mov_b64_e32 v[50:51], v[202:203]
	v_mov_b64_e32 v[52:53], v[204:205]
	v_mov_b64_e32 v[54:55], v[206:207]
	v_mov_b64_e32 v[56:57], v[208:209]
	v_fmamk_f32 v58, v58, 0x3a800000, v192
	v_mul_f32_e32 v59, 0x4b800000, v58
	v_cmp_gt_f32_e32 vcc, s93, v58
	s_nop 1
	v_cndmask_b32_e32 v58, v58, v59, vcc
	v_rsq_f32_e32 v58, v58
	s_nop 0
	v_mul_f32_e32 v59, 0x45800000, v58
	v_cndmask_b32_e32 v58, v58, v59, vcc
	v_pk_mul_f32 v[44:45], v[44:45], v[58:59] op_sel_hi:[1,0]
	v_pk_mul_f32 v[46:47], v[46:47], v[58:59] op_sel_hi:[1,0]
	v_pk_mul_f32 v[60:61], v[40:41], v[58:59] op_sel_hi:[1,0]
	v_pk_mul_f32 v[62:63], v[42:43], v[58:59] op_sel_hi:[1,0]
	v_pk_mul_f32 v[42:43], v[52:53], v[46:47]
	v_pk_mul_f32 v[40:41], v[50:51], v[44:45]
	v_pk_mul_f32 v[46:47], v[56:57], v[62:63]
	v_pk_mul_f32 v[44:45], v[54:55], v[60:61]
	global_store_dwordx4 v[48:49], v[40:43], off
	global_store_dwordx4 v[48:49], v[44:47], off offset:16
	v_mov_b64_e32 v[40:41], v[210:211]
	v_mov_b64_e32 v[42:43], v[212:213]
	s_nop 0
	v_mov_b64_e32 v[44:45], v[214:215]
	v_mov_b64_e32 v[46:47], v[216:217]
	v_pk_mul_f32 v[38:39], v[38:39], v[58:59] op_sel_hi:[1,0]
	v_pk_mul_f32 v[50:51], v[162:163], v[58:59] op_sel_hi:[1,0]
	v_pk_mul_f32 v[52:53], v[34:35], v[58:59] op_sel_hi:[1,0]
	v_pk_mul_f32 v[54:55], v[36:37], v[58:59] op_sel_hi:[1,0]
	v_pk_mul_f32 v[34:35], v[40:41], v[50:51]
	v_pk_mul_f32 v[36:37], v[42:43], v[38:39]
	v_pk_mul_f32 v[38:39], v[44:45], v[54:55]
	v_pk_mul_f32 v[40:41], v[46:47], v[52:53]
	global_store_dwordx4 v[48:49], v[34:37], off offset:512
	global_store_dwordx4 v[48:49], v[38:41], off offset:528
	v_mov_b32_e32 v42, v230
	s_nop 0
	v_mov_b64_e32 v[34:35], v[202:203]
	v_mov_b64_e32 v[36:37], v[204:205]
	v_mov_b64_e32 v[38:39], v[206:207]
	v_mov_b64_e32 v[40:41], v[208:209]
	v_fmamk_f32 v42, v42, 0x3a800000, v192
	v_mul_f32_e32 v43, 0x4b800000, v42
	v_cmp_gt_f32_e32 vcc, s93, v42
	s_nop 1
	v_cndmask_b32_e32 v42, v42, v43, vcc
	v_rsq_f32_e32 v42, v42
	s_nop 0
	v_mul_f32_e32 v43, 0x45800000, v42
	v_cndmask_b32_e32 v42, v42, v43, vcc
	v_pk_mul_f32 v[28:29], v[28:29], v[42:43] op_sel_hi:[1,0]
	v_pk_mul_f32 v[30:31], v[30:31], v[42:43] op_sel_hi:[1,0]
	v_pk_mul_f32 v[44:45], v[24:25], v[42:43] op_sel_hi:[1,0]
	v_pk_mul_f32 v[46:47], v[26:27], v[42:43] op_sel_hi:[1,0]
	v_pk_mul_f32 v[26:27], v[36:37], v[30:31]
	v_pk_mul_f32 v[24:25], v[34:35], v[28:29]
	v_pk_mul_f32 v[30:31], v[40:41], v[46:47]
	v_pk_mul_f32 v[28:29], v[38:39], v[44:45]
	global_store_dwordx4 v[32:33], v[24:27], off
	global_store_dwordx4 v[32:33], v[28:31], off offset:16
	v_mov_b64_e32 v[24:25], v[210:211]
	v_mov_b64_e32 v[26:27], v[212:213]
	s_nop 0
	v_mov_b64_e32 v[28:29], v[214:215]
	v_mov_b64_e32 v[30:31], v[216:217]
	v_pk_mul_f32 v[22:23], v[22:23], v[42:43] op_sel_hi:[1,0]
	v_pk_mul_f32 v[34:35], v[164:165], v[42:43] op_sel_hi:[1,0]
	v_pk_mul_f32 v[36:37], v[18:19], v[42:43] op_sel_hi:[1,0]
	v_pk_mul_f32 v[38:39], v[20:21], v[42:43] op_sel_hi:[1,0]
	v_pk_mul_f32 v[18:19], v[24:25], v[34:35]
	v_pk_mul_f32 v[20:21], v[26:27], v[22:23]
	v_pk_mul_f32 v[22:23], v[28:29], v[38:39]
	v_pk_mul_f32 v[24:25], v[30:31], v[36:37]
	global_store_dwordx4 v[32:33], v[18:21], off offset:512
	global_store_dwordx4 v[32:33], v[22:25], off offset:528
	v_mov_b32_e32 v26, v231
	s_nop 0
	v_mov_b64_e32 v[18:19], v[202:203]
	v_mov_b64_e32 v[20:21], v[204:205]
	v_mov_b64_e32 v[22:23], v[206:207]
	v_mov_b64_e32 v[24:25], v[208:209]
	v_fmamk_f32 v26, v26, 0x3a800000, v192
	v_mul_f32_e32 v27, 0x4b800000, v26
	v_cmp_gt_f32_e32 vcc, s93, v26
	s_nop 1
	v_cndmask_b32_e32 v26, v26, v27, vcc
	v_rsq_f32_e32 v26, v26
	s_nop 0
	v_mul_f32_e32 v27, 0x45800000, v26
	v_cndmask_b32_e32 v26, v26, v27, vcc
	v_pk_mul_f32 v[12:13], v[12:13], v[26:27] op_sel_hi:[1,0]
	v_pk_mul_f32 v[14:15], v[14:15], v[26:27] op_sel_hi:[1,0]
	v_pk_mul_f32 v[28:29], v[8:9], v[26:27] op_sel_hi:[1,0]
	v_pk_mul_f32 v[30:31], v[10:11], v[26:27] op_sel_hi:[1,0]
	v_pk_mul_f32 v[10:11], v[20:21], v[14:15]
	v_pk_mul_f32 v[8:9], v[18:19], v[12:13]
	v_pk_mul_f32 v[14:15], v[24:25], v[30:31]
	v_pk_mul_f32 v[12:13], v[22:23], v[28:29]
	global_store_dwordx4 v[16:17], v[8:11], off
	global_store_dwordx4 v[16:17], v[12:15], off offset:16
	v_mov_b64_e32 v[8:9], v[210:211]
	v_mov_b64_e32 v[10:11], v[212:213]
	s_nop 0
	v_mov_b64_e32 v[12:13], v[214:215]
	v_mov_b64_e32 v[14:15], v[216:217]
	v_pk_mul_f32 v[6:7], v[6:7], v[26:27] op_sel_hi:[1,0]
	v_pk_mul_f32 v[4:5], v[4:5], v[26:27] op_sel_hi:[1,0]
	s_andn2_b64 vcc, exec, s[40:41]
	v_pk_mul_f32 v[18:19], v[2:3], v[26:27] op_sel_hi:[1,0]
	v_pk_mul_f32 v[20:21], v[0:1], v[26:27] op_sel_hi:[1,0]
	v_pk_mul_f32 v[0:1], v[8:9], v[4:5]
	v_pk_mul_f32 v[2:3], v[10:11], v[6:7]
	v_pk_mul_f32 v[4:5], v[12:13], v[20:21]
	v_pk_mul_f32 v[6:7], v[14:15], v[18:19]
	global_store_dwordx4 v[16:17], v[0:3], off offset:512
	global_store_dwordx4 v[16:17], v[4:7], off offset:528
	s_cbranch_vccnz .LBB0_779
	s_andn2_b64 vcc, exec, s[10:11]
	s_cbranch_vccnz .LBB0_778
	s_barrier
	s_branch .LBB0_778
